# stacked version plus the forget-gate cumsum stores written through (less dirty data for the P1->P2 seam's write-back on XCD 0/1)
# baseline (speedup 1.0000x reference)
; #define LAS __attribute__((address_space(3)))
; __device__ __forceinline__ void cumsum_bh(const float* logf_, float* cc, int bh, LAS unsigned char* lds, int tid, int lane, int wave) {
;     LAS float* wt = (LAS float*)lds;
;     const float* src = logf_ + (size_t)bh * SEQ + tid * 8; float* dst = cc + (size_t)bh * SEQ + tid * 8;
;     f32x4 a = *(const f32x4*)src, b = *(const f32x4*)(src + 4);
;     a.y += a.x; a.z += a.y; a.w += a.z; b.x += a.w; b.y += b.x; b.z += b.y; b.w += b.z;
;     float tot = b.w, inc = tot;
; #pragma unroll
;     for (int o = 1; o < 64; o <<= 1) { const float n = __shfl_up(inc, o); if (lane >= o) inc += n; }
;     if (lane == 63) wt[wave] = inc;
;     __syncthreads();
;     float base = inc - tot;
;     for (int w = 0; w < wave; ++w) base += wt[w];
;     a = a + base; b = b + base;
;     *(f32x4*)dst = a; *(f32x4*)(dst + 4) = b;
;     __syncthreads();
.LBB0_80:
	s_lshl_b64 s[66:67], s[64:65], 12
	s_add_i32 s64, s64, s3
	v_lshl_add_u64 v[24:25], s[66:67], 2, v[8:9]
	v_pk_add_f32 v[22:23], v[12:13], v[14:15] op_sel_hi:[1,0]
	v_pk_add_f32 v[20:21], v[2:3], v[14:15] op_sel_hi:[1,0]
	s_cmp_gt_i32 s64, 63
	v_pk_add_f32 v[12:13], v[10:11], v[14:15] op_sel_hi:[1,0]
	v_pk_add_f32 v[10:11], v[4:5], v[14:15] op_sel_hi:[1,0]
	global_store_dwordx4 v[24:25], v[20:23], off sc0 sc1
	global_store_dwordx4 v[24:25], v[10:13], off offset:16 sc0 sc1
	s_barrier
	s_cbranch_scc1 .LBB0_91
